# sample units start without waiting for the GEMM epilogue store acknowledgements (retire wait moved behind the sample-unit loop), FFN-down between-tiles retire removed; on top of cold-start variant
# speedup vs baseline: 1.0006x; 1.0006x over previous
; #define PG8_WAIT_V(n) asm volatile("s_waitcnt vmcnt(" #n ")" ::: "memory")
; #define PG8_BAR __builtin_amdgcn_s_barrier()
; template <class Epi, class Sched, bool ALIGN_EPI = false, bool SP2 = false>
; __device__ __forceinline__ void gemm_phase(PG8_LAS unsigned char* lds, const Gemm g, const Sched& S, const Epi& E, int wave_u) {
;     ...
;     PG8_WAIT_V(0);
;     if constexpr (!ALIGN_EPI) { if (wr == 0) PG8_BAR; }
;     PG8_BAR;
.LBB0_187:
	v_readlane_b32 s78, v255, 13
	v_readlane_b32 s79, v255, 14
	s_mov_b32 s92, s78
	v_readlane_b32 s64, v255, 16
	v_readlane_b32 s76, v255, 18
	v_readlane_b32 s78, v255, 20
	v_readlane_b32 s80, v255, 22
	v_readlane_b32 s82, v255, 24
	v_readlane_b32 s86, v255, 26
	v_readlane_b32 s88, v255, 28
	v_readlane_b32 s52, v251, 39
	v_readlane_b32 s30, v255, 60
	v_readlane_b32 s75, v255, 15
	v_readlane_b32 s65, v255, 17
	v_readlane_b32 s77, v255, 19
	v_readlane_b32 s79, v255, 21
	v_readlane_b32 s81, v255, 23
	v_readlane_b32 s83, v255, 25
	v_readlane_b32 s87, v255, 27
	v_readlane_b32 s89, v255, 29
	v_readlane_b32 s53, v251, 40
	v_readlane_b32 s31, v255, 61
	s_barrier

; __device__ __forceinline__ int lane_id_now() { int l; asm volatile("v_mbcnt_lo_u32_b32 %0, -1, 0\n\tv_mbcnt_hi_u32_b32 %0, -1, %0" : "=v"(l)); return l; }
; template <class Epi>
; __device__ __forceinline__ void mini_ring(PG8_LAS unsigned char* lds, const bf16_t* A, const bf16_t* Bt, int K, const Epi& E, int mu, int wave_u) {
;     ...
;     int tid_ = wave_u * 64 + lane_id_now(); asm volatile("" : "+v"(tid_));
;     const int tid = tid_, w = __builtin_amdgcn_readfirstlane(tid >> 6), lane = tid & 63, fr = lane & 15, fq = lane >> 4;
;     const int rsel = mu & 1, wc = (mu >> 1) & 3, j = mu >> 3, nchunk = K >> 6;
;     epi_prefetch(E, MP_ / BM, j, (unsigned)__builtin_amdgcn_readfirstlane((int)((unsigned)(size_t)lds + (unsigned)EPV_OFF + (unsigned)w * 256u)), tid);
;     const char* src[2];
; #pragma unroll
;     for (int i = 0; i < 2; ++i) { const int P = tid + 512 * i, row = P >> 3, q = (P & 7) ^ (row & 7);
;         const bf16_t* rp = row < 64 ? A + (size_t)(MP_ + 64 * rsel + row) * K : Bt + (size_t)(256 * j + 128 * ((row - 64) >> 5) + 32 * wc + perm32((row - 64) & 31)) * K;
;         src[i] = (const char*)rp + 16 * q; }
;     ...
;     asm volatile("s_waitcnt lgkmcnt(0)" ::: "memory"); __builtin_amdgcn_s_barrier(); asm volatile("" ::: "memory");
.LBB0_190:
	s_waitcnt vmcnt(0) lgkmcnt(0)
	s_barrier
	s_add_i32 s7, s18, s7
	s_cmpk_lt_u32 s7, 0x60
	s_cbranch_scc0 .LBB0_251
.LBB0_191:
	v_mbcnt_lo_u32_b32 v0, -1, 0
	v_mbcnt_hi_u32_b32 v0, -1, v0
	v_readlane_b32 s10, v255, 45
	v_add_u32_e32 v2, s75, v0
	s_lshr_b32 s20, s7, 3
	v_readfirstlane_b32 s19, v2
	s_ashr_i32 s22, s19, 6
	s_lshl_b32 s0, s22, 8
	s_add_i32 s0, s0, 0
	v_ashrrev_i32_e32 v3, 31, v2
	s_add_i32 s1, s0, 0x20400
	v_lshlrev_b64 v[4:5], 2, v[2:3]
	v_lshl_add_u64 v[6:7], s[12:13], 0, v[4:5]
	s_mov_b32 s2, m0
	s_mov_b32 m0, s1
	s_nop 0
	global_load_lds_dword v[6:7], off
	s_mov_b32 m0, s2
	s_movk_i32 s1, 0x100
	v_cmp_gt_i32_e32 vcc, s1, v2
	v_readlane_b32 s11, v255, 46
	s_lshl_b32 s2, s20, 8
	v_cndmask_b32_e64 v0, v219, 0, vcc
	v_lshl_add_u64 v[6:7], s[10:11], 0, v[0:1]
	v_lshl_add_u64 v[6:7], s[2:3], 2, v[6:7]
	v_lshl_add_u64 v[4:5], v[6:7], 0, v[4:5]
	s_add_i32 s0, s0, 0x20c00
	s_mov_b32 s1, m0
	s_mov_b32 m0, s0
	s_nop 0
	global_load_lds_dword v[4:5], off
	s_mov_b32 m0, s1
	s_lshl_b32 s0, s7, 4
	v_ashrrev_i32_e32 v3, 3, v2
	s_and_b32 s21, s0, 0x60
	v_cmp_lt_i32_e32 vcc, 63, v3
	s_and_saveexec_b64 s[0:1], vcc
	s_xor_b64 s[10:11], exec, s[0:1]
	s_cbranch_execz .LBB0_193
	v_lshrrev_b32_e32 v6, 2, v3
	v_lshrrev_b32_e32 v0, 3, v2
	v_lshlrev_b32_e32 v5, 1, v3
	v_and_b32_e32 v6, 4, v6
	v_and_b32_e32 v5, 24, v5
	v_and_or_b32 v0, v0, 3, v6
	v_lshl_add_u32 v4, v3, 2, v220
	v_or3_b32 v0, v0, v5, s21
	v_and_b32_e32 v4, 0x7fffff80, v4
	v_or_b32_e32 v0, s2, v0
	v_add_u32_e32 v0, v0, v4
	v_mov_b64_e32 v[4:5], v[0:1]

; #define SEAM(k) do { XcdBarrier _b; _b.bar = (unsigned*)(args.ws + WS_CTL) + CW_BAR; _b.x = xb_xcc_id(); _b.st = (volatile LAS unsigned*)(F.lds + MISC_OFF) + 8; xcd_barrier(_b); } while (0)
; #define SEAM_LT(k) do { XcdBarrier _b; _b.bar = (unsigned*)(args.ws + WS_CTL) + CW_BAR; _b.x = xb_xcc_id(); _b.st = (volatile LAS unsigned*)(F.lds + MISC_OFF) + 8; xcd_barrier_light(_b, (const unsigned*)(args.ws + WS_CTL) + CW_NONLOC); } while (0)
; __global__ void __launch_bounds__(NWAVES * 64, 2) mk_fwd(Args args) {
;     ...
;                 { int Gq = F.G; asm volatile("" : "+s"(Gq)); const int nmu = g.N >> 5, mfirst = (nmu <= Gq / 2 || Gq < 256) ? (Gq - nmu > 0 ? Gq - nmu : 0) : Gq / 2; for (int mu = (int)blockIdx.x - mfirst; mu >= 0 && mu < nmu; mu += Gq - mfirst) pg8::mini_ring(F.lds + RING_OFF, g.A, g.Bt, g.K, E, mu, F.wave); } }
;             if (l == 0) SEAM(pb); else SEAM_LT(pb);
.LBB0_251:
	s_waitcnt vmcnt(0)
	s_barrier
	s_mov_b64 s[10:11], 0

; #define PG8_WAIT_V(n) asm volatile("s_waitcnt vmcnt(" #n ")" ::: "memory")
; #define PG8_BAR __builtin_amdgcn_s_barrier()
; template <class Epi, class Sched, bool ALIGN_EPI = false, bool SP2 = false>
; __device__ __forceinline__ void gemm_phase(PG8_LAS unsigned char* lds, const Gemm g, const Sched& S, const Epi& E, int wave_u) {
;     ...
;     PG8_WAIT_V(0);
;     if constexpr (!ALIGN_EPI) { if (wr == 0) PG8_BAR; }
;     PG8_BAR;
.LBB0_337:
	v_readlane_b32 s64, v255, 16
	v_readlane_b32 s76, v255, 18
	v_readlane_b32 s78, v255, 20
	v_readlane_b32 s80, v255, 22
	v_readlane_b32 s82, v255, 24
	v_readlane_b32 s86, v255, 26
	v_readlane_b32 s88, v255, 28
	v_readlane_b32 s84, v251, 41
	v_readlane_b32 s90, v251, 61
	v_readlane_b32 s30, v255, 60
	v_readlane_b32 s65, v255, 17
	v_readlane_b32 s77, v255, 19
	v_readlane_b32 s79, v255, 21
	v_readlane_b32 s81, v255, 23
	v_readlane_b32 s83, v255, 25
	v_readlane_b32 s87, v255, 27
	v_readlane_b32 s89, v255, 29
	v_readlane_b32 s85, v251, 42
	v_readlane_b32 s91, v251, 62
	v_readlane_b32 s31, v255, 61
	s_barrier

; __device__ __forceinline__ int lane_id_now() { int l; asm volatile("v_mbcnt_lo_u32_b32 %0, -1, 0\n\tv_mbcnt_hi_u32_b32 %0, -1, %0" : "=v"(l)); return l; }
; template <class Epi>
; __device__ __forceinline__ void mini_ring(PG8_LAS unsigned char* lds, const bf16_t* A, const bf16_t* Bt, int K, const Epi& E, int mu, int wave_u) {
;     ...
;     int tid_ = wave_u * 64 + lane_id_now(); asm volatile("" : "+v"(tid_));
;     const int tid = tid_, w = __builtin_amdgcn_readfirstlane(tid >> 6), lane = tid & 63, fr = lane & 15, fq = lane >> 4;
;     const int rsel = mu & 1, wc = (mu >> 1) & 3, j = mu >> 3, nchunk = K >> 6;
;     epi_prefetch(E, MP_ / BM, j, (unsigned)__builtin_amdgcn_readfirstlane((int)((unsigned)(size_t)lds + (unsigned)EPV_OFF + (unsigned)w * 256u)), tid);
;     const char* src[2];
; #pragma unroll
;     for (int i = 0; i < 2; ++i) { const int P = tid + 512 * i, row = P >> 3, q = (P & 7) ^ (row & 7);
;         const bf16_t* rp = row < 64 ? A + (size_t)(MP_ + 64 * rsel + row) * K : Bt + (size_t)(256 * j + 128 * ((row - 64) >> 5) + 32 * wc + perm32((row - 64) & 31)) * K;
;         src[i] = (const char*)rp + 16 * q; }
;     ...
;     asm volatile("s_waitcnt lgkmcnt(0)" ::: "memory"); __builtin_amdgcn_s_barrier(); asm volatile("" ::: "memory");
.LBB0_340:
	s_waitcnt vmcnt(0) lgkmcnt(0)
	s_barrier
	s_add_i32 s17, s18, s17
	s_cmpk_gt_u32 s17, 0x5f
	s_cbranch_scc1 .LBB0_458
.LBB0_341:
	v_mbcnt_lo_u32_b32 v0, -1, 0
	v_mbcnt_hi_u32_b32 v0, -1, v0
	v_readlane_b32 s10, v255, 45
	v_add_u32_e32 v2, s75, v0
	s_lshr_b32 s7, s17, 3
	v_readfirstlane_b32 s19, v2
	s_ashr_i32 s21, s19, 6
	s_lshl_b32 s0, s21, 8
	s_add_i32 s0, s0, 0
	v_ashrrev_i32_e32 v3, 31, v2
	s_add_i32 s1, s0, 0x20400
	v_lshlrev_b64 v[4:5], 2, v[2:3]
	v_lshl_add_u64 v[6:7], s[12:13], 0, v[4:5]
	s_mov_b32 s2, m0
	s_mov_b32 m0, s1
	s_nop 0
	global_load_lds_dword v[6:7], off
	s_mov_b32 m0, s2
	s_movk_i32 s1, 0x100
	v_cmp_gt_i32_e32 vcc, s1, v2
	v_readlane_b32 s11, v255, 46
	s_lshl_b32 s2, s7, 8
	v_cndmask_b32_e64 v0, v219, 0, vcc
	v_lshl_add_u64 v[6:7], s[10:11], 0, v[0:1]
	v_lshl_add_u64 v[6:7], s[2:3], 2, v[6:7]
	v_lshl_add_u64 v[4:5], v[6:7], 0, v[4:5]
	s_add_i32 s0, s0, 0x20c00
	s_mov_b32 s1, m0
	s_mov_b32 m0, s0
	s_nop 0
	global_load_lds_dword v[4:5], off
	s_mov_b32 m0, s1
	s_lshl_b32 s0, s17, 4
	v_ashrrev_i32_e32 v3, 3, v2
	s_and_b32 s20, s0, 0x60
	v_cmp_lt_i32_e32 vcc, 63, v3
	s_and_saveexec_b64 s[0:1], vcc
	s_xor_b64 s[10:11], exec, s[0:1]
	s_cbranch_execz .LBB0_343
	v_lshrrev_b32_e32 v6, 2, v3
	v_lshrrev_b32_e32 v0, 3, v2
	v_lshlrev_b32_e32 v5, 1, v3
	v_and_b32_e32 v6, 4, v6
	v_and_b32_e32 v5, 24, v5
	v_and_or_b32 v0, v0, 3, v6
	v_lshl_add_u32 v4, v3, 2, v220
	v_or3_b32 v0, v0, v5, s20
	v_and_b32_e32 v4, 0x7fffff80, v4
	v_or_b32_e32 v0, s2, v0
	v_add_u32_e32 v0, v0, v4
	v_mov_b64_e32 v[4:5], v[0:1]

; __global__ void __launch_bounds__(NWAVES * 64, 2) mk_fwd(Args args) {
;     ...
;                 { int Gq = F.G; asm volatile("" : "+s"(Gq)); const int nmu = g.N >> 5, mfirst = (nmu <= Gq / 2 || Gq < 256) ? (Gq - nmu > 0 ? Gq - nmu : 0) : Gq / 2; for (int mu = (int)blockIdx.x - mfirst; mu >= 0 && mu < nmu; mu += Gq - mfirst) pg8::mini_ring(F.lds + RING_OFF, g.A, g.Bt, g.K, E, mu, F.wave);
;                   if (l == 0) { const int w2s = (F.G == 256) ? P_IW2 : 0; if (mfirst > 0) { if ((int)blockIdx.x < mfirst) p_convert_tail(F, args, P_IIN, P_ILAYER - w2s, (int)blockIdx.x, mfirst); } else p_convert_tail(F, args, P_IIN, P_ILAYER - w2s, (int)blockIdx.x, F.G); } } }
.LBB0_458:
	s_waitcnt vmcnt(0)
	s_barrier
	v_readlane_b32 s0, v255, 62
	s_cmp_eq_u32 s0, 0
	v_readlane_b32 s1, v255, 63
	s_cbranch_scc0 .LBB0_556
	s_cmpk_lt_i32 s16, 0x61
	s_mov_b64 s[10:11], -1
	s_cbranch_scc0 .LBB0_507
	v_readlane_b32 s0, v250, 28
	v_mbcnt_lo_u32_b32 v0, -1, 0
	v_mbcnt_hi_u32_b32 v0, -1, v0
	v_readlane_b32 s1, v250, 29
	v_add_u32_e32 v0, s75, v0
	s_andn2_b64 vcc, exec, s[0:1]
	s_cbranch_vccnz .LBB0_506
	v_readlane_b32 s0, v250, 31
	v_readlane_b32 s1, v250, 32
	s_mov_b64 s[28:29], -1
	s_and_b64 vcc, exec, s[0:1]
	s_cbranch_vccz .LBB0_468
	v_readlane_b32 s0, v250, 33
	v_readlane_b32 s1, v250, 34
	s_and_b64 vcc, exec, s[0:1]
	s_cbranch_vccz .LBB0_465
	v_readlane_b32 s0, v250, 35
	v_readlane_b32 s1, v250, 36
	s_andn2_b64 vcc, exec, s[0:1]
	s_mov_b64 s[28:29], 0
	s_cbranch_vccz .LBB0_464
	s_getpc_b64 s[98:99]

; __device__ __forceinline__ f32x4 zero4_pk() { f32x2_z a, b; asm volatile("v_pk_mov_b32 %0, 0, 0" : "=v"(a)); asm volatile("v_pk_mov_b32 %0, 0, 0" : "=v"(b)); return (f32x4){a.x, a.y, b.x, b.y}; }
; #define PG8_WAIT_V(n) asm volatile("s_waitcnt vmcnt(" #n ")" ::: "memory")
; #define PG8_BAR __builtin_amdgcn_s_barrier()
; template <class Epi, class Sched, bool ALIGN_EPI = false, bool SP2 = false>
; __device__ __forceinline__ void gemm_phase(PG8_LAS unsigned char* lds, const Gemm g, const Sched& S, const Epi& E, int wave_u) {
;     ...
;         if (!has_next) break;
; #pragma unroll
;         for (int a = 0; a < 2; ++a)
; #pragma unroll
;             for (int b = 0; b < 2; ++b)
; #pragma unroll
;                 for (int m = 0; m < 4; ++m)
; #pragma unroll
;                     for (int n = 0; n < 2; ++n) acc[a][b][m][n] = zero4_pk();
;         cur = nxt; cA = nA; cB = nB; ++ui;
;         if constexpr (ALIGN_EPI) { if (wr == 1) PG8_BAR; }
;     }
;     PG8_WAIT_V(0);
;     if constexpr (!ALIGN_EPI) { if (wr == 0) PG8_BAR; }
;     PG8_BAR;
.LBB0_1449:
	s_or_b64 exec, exec, s[14:15]
	s_and_b64 vcc, exec, s[12:13]
	s_mov_b64 s[12:13], -1
	s_cbranch_vccnz .LBB0_1416
	s_andn2_b64 vcc, exec, s[16:17]
	v_pk_mov_b32 v[170:171], 0, 0
	v_pk_mov_b32 v[172:173], 0, 0
	v_pk_mov_b32 v[166:167], 0, 0
	v_pk_mov_b32 v[168:169], 0, 0
	v_pk_mov_b32 v[142:143], 0, 0
	v_pk_mov_b32 v[144:145], 0, 0
	v_pk_mov_b32 v[134:135], 0, 0
	v_pk_mov_b32 v[136:137], 0, 0
	v_pk_mov_b32 v[118:119], 0, 0
	v_pk_mov_b32 v[120:121], 0, 0
	v_pk_mov_b32 v[110:111], 0, 0
	v_pk_mov_b32 v[112:113], 0, 0
	v_pk_mov_b32 v[94:95], 0, 0
	v_pk_mov_b32 v[96:97], 0, 0
	v_pk_mov_b32 v[86:87], 0, 0
	v_pk_mov_b32 v[88:89], 0, 0
	v_pk_mov_b32 v[154:155], 0, 0
	v_pk_mov_b32 v[156:157], 0, 0
	v_pk_mov_b32 v[150:151], 0, 0
	v_pk_mov_b32 v[152:153], 0, 0
	v_pk_mov_b32 v[130:131], 0, 0
	v_pk_mov_b32 v[132:133], 0, 0
	v_pk_mov_b32 v[126:127], 0, 0
	v_pk_mov_b32 v[128:129], 0, 0
	v_pk_mov_b32 v[106:107], 0, 0
	v_pk_mov_b32 v[108:109], 0, 0
	v_pk_mov_b32 v[102:103], 0, 0
	v_pk_mov_b32 v[104:105], 0, 0
	v_pk_mov_b32 v[82:83], 0, 0
	v_pk_mov_b32 v[84:85], 0, 0
	v_pk_mov_b32 v[78:79], 0, 0
	v_pk_mov_b32 v[80:81], 0, 0
	v_pk_mov_b32 v[70:71], 0, 0
	v_pk_mov_b32 v[72:73], 0, 0
	v_pk_mov_b32 v[66:67], 0, 0
	v_pk_mov_b32 v[68:69], 0, 0
	v_pk_mov_b32 v[46:47], 0, 0
	v_pk_mov_b32 v[48:49], 0, 0
	v_pk_mov_b32 v[42:43], 0, 0
	v_pk_mov_b32 v[44:45], 0, 0
	v_pk_mov_b32 v[30:31], 0, 0
	v_pk_mov_b32 v[32:33], 0, 0
	v_pk_mov_b32 v[26:27], 0, 0
	v_pk_mov_b32 v[28:29], 0, 0
	v_pk_mov_b32 v[14:15], 0, 0
	v_pk_mov_b32 v[16:17], 0, 0
	v_pk_mov_b32 v[10:11], 0, 0
	v_pk_mov_b32 v[12:13], 0, 0
	v_pk_mov_b32 v[58:59], 0, 0
	v_pk_mov_b32 v[60:61], 0, 0
	v_pk_mov_b32 v[54:55], 0, 0
	v_pk_mov_b32 v[56:57], 0, 0
	v_pk_mov_b32 v[38:39], 0, 0
	v_pk_mov_b32 v[40:41], 0, 0
	v_pk_mov_b32 v[34:35], 0, 0
	v_pk_mov_b32 v[36:37], 0, 0
	v_pk_mov_b32 v[22:23], 0, 0
	v_pk_mov_b32 v[24:25], 0, 0
	v_pk_mov_b32 v[18:19], 0, 0
	v_pk_mov_b32 v[20:21], 0, 0
	v_pk_mov_b32 v[6:7], 0, 0
	v_pk_mov_b32 v[8:9], 0, 0
	s_waitcnt lgkmcnt(1)
	v_pk_mov_b32 v[2:3], 0, 0
	s_waitcnt lgkmcnt(0)
	v_pk_mov_b32 v[4:5], 0, 0
	s_cbranch_vccnz .LBB0_1415
	s_barrier
	s_branch .LBB0_1415
.LBB0_1452:
	v_readlane_b32 s78, v255, 13
	v_readlane_b32 s79, v255, 14
	s_mov_b32 s92, s78
	v_readlane_b32 s64, v255, 16
	v_readlane_b32 s76, v255, 18
	v_readlane_b32 s78, v255, 20
	v_readlane_b32 s80, v255, 22
	v_readlane_b32 s82, v255, 24
	v_readlane_b32 s86, v255, 26
	v_readlane_b32 s88, v255, 28
	v_readlane_b32 s75, v255, 15
	v_readlane_b32 s65, v255, 17
	v_readlane_b32 s77, v255, 19
	v_readlane_b32 s79, v255, 21
	v_readlane_b32 s81, v255, 23
	v_readlane_b32 s83, v255, 25
	v_readlane_b32 s87, v255, 27
	v_readlane_b32 s89, v255, 29
	s_mov_b32 s96, 0x11000
	s_mov_b64 s[84:85], 0x100
	v_readlane_b32 s14, v255, 43
	v_readlane_b32 s15, v255, 45
	s_barrier

; __device__ __forceinline__ int lane_id_now() { int l; asm volatile("v_mbcnt_lo_u32_b32 %0, -1, 0\n\tv_mbcnt_hi_u32_b32 %0, -1, %0" : "=v"(l)); return l; }
; template <class Epi>
; __device__ __forceinline__ void mini_ring(PG8_LAS unsigned char* lds, const bf16_t* A, const bf16_t* Bt, int K, const Epi& E, int mu, int wave_u) {
;     ...
;     int tid_ = wave_u * 64 + lane_id_now(); asm volatile("" : "+v"(tid_));
;     const int tid = tid_, w = __builtin_amdgcn_readfirstlane(tid >> 6), lane = tid & 63, fr = lane & 15, fq = lane >> 4;
;     const int rsel = mu & 1, wc = (mu >> 1) & 3, j = mu >> 3, nchunk = K >> 6;
;     epi_prefetch(E, MP_ / BM, j, (unsigned)__builtin_amdgcn_readfirstlane((int)((unsigned)(size_t)lds + (unsigned)EPV_OFF + (unsigned)w * 256u)), tid);
;     const char* src[2];
; #pragma unroll
;     for (int i = 0; i < 2; ++i) { const int P = tid + 512 * i, row = P >> 3, q = (P & 7) ^ (row & 7);
;         const bf16_t* rp = row < 64 ? A + (size_t)(MP_ + 64 * rsel + row) * K : Bt + (size_t)(256 * j + 128 * ((row - 64) >> 5) + 32 * wc + perm32((row - 64) & 31)) * K;
;         src[i] = (const char*)rp + 16 * q; }
.LBB0_1458:
	v_mbcnt_lo_u32_b32 v0, -1, 0
	v_mbcnt_hi_u32_b32 v0, -1, v0
	s_bfe_u32 s15, s44, 0x20001
	s_waitcnt lgkmcnt(1)
	v_add_u32_e32 v2, s75, v0
	v_mov_b32_e32 v0, s46
	v_readfirstlane_b32 s14, v2
	s_ashr_i32 s7, s14, 6
	s_lshl_b32 s0, s7, 8
	s_add_i32 s0, s0, 0
	v_ashrrev_i32_e32 v3, 31, v2
	s_add_i32 s1, s0, 0x20400
	s_waitcnt lgkmcnt(0)
	v_lshlrev_b64 v[4:5], 2, v[2:3]
	v_lshl_add_u64 v[6:7], s[60:61], 0, v[4:5]
	s_mov_b32 s2, m0
	s_mov_b32 m0, s1
	s_nop 0
	global_load_lds_dword v[6:7], off
	s_mov_b32 m0, s2
	s_movk_i32 s1, 0x100
	v_mov_b32_e32 v3, s59
	v_cmp_gt_i32_e32 vcc, s1, v2
	s_lshl_b32 s1, s44, 5
	s_and_b32 s16, s1, 0x300
	v_cndmask_b32_e32 v7, v0, v3, vcc
	v_mov_b32_e32 v0, s45
	v_mov_b32_e32 v3, s58
	v_cndmask_b32_e32 v6, v0, v3, vcc
	s_lshl_b32 s2, s16, 2
	v_lshl_add_u64 v[6:7], v[6:7], 0, s[2:3]
	s_add_i32 s0, s0, 0x20c00
	v_lshl_add_u64 v[4:5], v[6:7], 0, v[4:5]
	s_mov_b32 s1, m0
	s_mov_b32 m0, s0
	s_nop 0
	global_load_lds_dword v[4:5], off
	s_mov_b32 m0, s1
	s_and_b32 s0, s44, 24
	s_or_b32 s0, s15, s0
	v_ashrrev_i32_e32 v3, 3, v2
	s_lshl_b32 s0, s0, 5
	v_cmp_lt_i32_e32 vcc, 63, v3
	s_and_saveexec_b64 s[10:11], vcc
	s_xor_b64 s[10:11], exec, s[10:11]
	s_cbranch_execz .LBB0_1460
	v_lshrrev_b32_e32 v6, 2, v3
	v_lshrrev_b32_e32 v0, 3, v2
	v_lshlrev_b32_e32 v5, 1, v3
	v_and_b32_e32 v6, 4, v6
	v_lshl_add_u32 v4, v3, 2, v220
	v_and_b32_e32 v5, 24, v5
	v_and_or_b32 v0, v0, 3, v6
	v_and_b32_e32 v4, 0x7fffff80, v4
	v_or3_b32 v0, v0, v5, s0
	v_add_u32_e32 v0, v0, v4
	v_mov_b64_e32 v[4:5], v[0:1]

; __global__ void __launch_bounds__(NWAVES * 64, 2) mk_fwd(Args args) {
;     ...
;                 { int Gq = F.G; asm volatile("" : "+s"(Gq)); const int nmu = g.N >> 5, mfirst = (nmu <= Gq / 2 || Gq < 256) ? (Gq - nmu > 0 ? Gq - nmu : 0) : Gq / 2; for (int mu = (int)blockIdx.x - mfirst; mu >= 0 && mu < nmu; mu += Gq - mfirst) pg8::mini_ring(F.lds + RING_OFF, g.A, g.Bt, g.K, E, mu, F.wave);
;                   if (l < 3) { if (mfirst > 0) { if ((int)blockIdx.x < mfirst) { p_convert_tail(F, args, (l + 1) * P_ILAYER, (l + 2) * P_ILAYER - ((F.G == 256) ? (l == 0 ? 768 : 1792) : 0), (int)blockIdx.x, mfirst); if (l == 0) p_state_copies_tail(F, args, (int)blockIdx.x, mfirst); } }
;                   else { p_convert_tail(F, args, (l + 1) * P_ILAYER, (l + 2) * P_ILAYER - ((F.G == 256) ? (l == 0 ? 768 : 1792) : 0), (int)blockIdx.x, F.G); if (l == 0) p_state_copies_tail(F, args, (int)blockIdx.x, F.G); } } } }
.LBB0_1546:
	s_waitcnt vmcnt(0)
	s_barrier
	v_readlane_b32 s0, v255, 62
	s_cmp_lg_u32 s0, 3
	s_mov_b64 s[10:11], -1
	v_readlane_b32 s1, v255, 63
	s_cbranch_scc0 .LBB0_1764
	s_cmp_lt_i32 s29, 33
	s_cbranch_scc0 .LBB0_1627
	v_readlane_b32 s0, v255, 62
	v_readlane_b32 s1, v255, 63
	s_mul_i32 s2, s0, 0x1880
	v_readlane_b32 s0, v255, 53
	v_readlane_b32 s1, v255, 54
	s_and_b64 s[0:1], s[0:1], exec
	s_movk_i32 s0, 0xfd00
	s_cselect_b32 s7, s0, 0xfffff900
	v_readlane_b32 s0, v252, 62
	v_readlane_b32 s1, v252, 63
	s_and_b64 s[0:1], s[0:1], exec
	s_cselect_b32 s0, s7, 0
	s_add_i32 s7, s2, s0
	v_readlane_b32 s0, v253, 60
	s_addk_i32 s7, 0x3100
	v_mbcnt_lo_u32_b32 v0, -1, 0
	v_mbcnt_hi_u32_b32 v0, -1, v0
	s_add_i32 s29, s0, s2
	v_add_u32_e32 v0, s75, v0
	s_cmp_ge_i32 s29, s7
	s_cbranch_scc1 .LBB0_1601
	s_mul_hi_i32 s0, s29, 0x5397829d
	s_lshr_b32 s1, s0, 31
	s_ashr_i32 s0, s0, 11
	s_add_i32 s26, s0, s1
	s_mul_i32 s1, s26, 0x1880
	s_ashr_i32 s30, s26, 1
	s_and_b32 s0, s26, 1
	s_sub_i32 s1, s29, s1
	s_ashr_i32 s27, s26, 31
	s_mul_i32 s10, s26, 0x1880000
	v_readlane_b32 s11, v253, 5
	s_mul_hi_i32 s2, s26, 0x1880000
	s_add_u32 s22, s11, s10
	v_readlane_b32 s10, v253, 6
	s_addc_u32 s23, s10, s2
	s_mul_i32 s10, s26, 0x11000
	v_readlane_b32 s11, v253, 7
	s_mul_hi_i32 s2, s26, 0x11000
	s_add_u32 s24, s11, s10
	v_readlane_b32 s10, v253, 8
	s_addc_u32 s25, s10, s2
	s_cmpk_gt_i32 s1, 0x5ff
	s_mov_b64 s[46:47], -1
	s_cbranch_scc0 .LBB0_1558
	s_cmpk_gt_u32 s1, 0x7ff
	s_cbranch_scc0 .LBB0_1555
	s_mov_b64 s[18:19], -1
	s_cmpk_gt_u32 s1, 0x12ff
	s_mul_hi_i32 s2, s26, 0xb00000
	s_mul_i32 s13, s26, 0xb00000
	s_cbranch_scc0 .LBB0_1553
	v_readlane_b32 s56, v253, 26
	v_readlane_b32 s57, v253, 27
	s_add_u32 s10, s56, s13
	s_addc_u32 s11, s57, s2
	s_add_u32 s14, s22, 0x1300000
	s_addc_u32 s15, s23, 0
	s_lshl_b32 s16, s1, 1
	s_lshl_b32 s12, s1, 5
	s_and_b32 s16, s16, 0x7fffffc0
	v_readlane_b32 s58, v253, 28
	v_readlane_b32 s59, v253, 29
	v_readlane_b32 s60, v253, 30
	v_readlane_b32 s61, v253, 31
	v_readlane_b32 s62, v253, 32
	v_readlane_b32 s63, v253, 33
	s_and_b32 s12, s12, 0x3e0
	s_addk_i32 s16, 0xda00
	s_mov_b64 s[18:19], 0
